# v35 + nt (non-temporal) hint on the in-proj and FFN1 epilogue output stores to keep GEMM operands in L2
# speedup vs baseline: 1.0004x; 1.0004x over previous
; __device__ __forceinline__ unsigned cvt_pk_bf16(float lo, float hi) { unsigned r; asm volatile("v_cvt_pk_bf16_f32 %0, %1, %2" : "=v"(r) : "v"(lo), "v"(hi)); return r; }
;     DI void operator()(const pg8::f32x4 (&acc)[2][2][4][2], const pg8::Unit& u, int wr, int wc, int fr, int fq) const {
;         const int row0 = u.pm * 256 + wr * 64 + fr, col0 = u.pn * 256 + wc * 32 + 8 * fq;
; #pragma unroll
;         for (int ai = 0; ai < 2; ++ai)
; #pragma unroll
;             for (int m = 0; m < 4; ++m) { bf16* rowp = O + (size_t)(row0 + ai * 128 + m * 16) * ldc + col0;
; #pragma unroll
;                 for (int bj = 0; bj < 2; ++bj) { const pg8::f32x4 v0 = acc[ai][bj][m][0], v1 = acc[ai][bj][m][1];
;                     v4u w; w.x = pg8::cvt_pk_bf16(v0[0], v0[1]); w.y = pg8::cvt_pk_bf16(v0[2], v0[3]); w.z = pg8::cvt_pk_bf16(v1[0], v1[1]); w.w = pg8::cvt_pk_bf16(v1[2], v1[3]);
;                     *(v4u*)(rowp + bj * 128) = w; } }
.LBB0_241:
	v_lshl_or_b32 v140, s37, 8, v144
	v_lshl_add_u32 v148, s38, 8, v142
	v_ashrrev_i32_e32 v141, 31, v140
	v_mov_b64_e32 v[138:139], s[4:5]
	s_movk_i32 s11, 0x1c00
	v_mad_i64_i32 v[146:147], s[18:19], v148, s11, v[138:139]
	v_lshlrev_b64 v[140:141], 1, v[140:141]
	v_lshl_add_u64 v[146:147], v[146:147], 0, v[140:141]
	v_cvt_pk_bf16_f32 v124, v124, v125
	v_cvt_pk_bf16_f32 v125, v126, v127
	v_cvt_pk_bf16_f32 v126, v120, v121
	v_cvt_pk_bf16_f32 v127, v122, v123
	global_store_dwordx4 v[146:147], v[124:127], off nt
	v_cvt_pk_bf16_f32 v112, v112, v113
	v_cvt_pk_bf16_f32 v113, v114, v115
	v_cvt_pk_bf16_f32 v114, v104, v105
	v_or_b32_e32 v104, 16, v148
	v_mad_i64_i32 v[104:105], s[18:19], v104, s11, v[138:139]
	v_cvt_pk_bf16_f32 v115, v106, v107
	global_store_dwordx4 v[146:147], v[112:115], off offset:256 nt
	s_andn2_b64 vcc, exec, s[0:1]
	s_mov_b64 s[0:1], -1
	v_lshl_add_u64 v[112:113], v[104:105], 0, v[140:141]
	v_cvt_pk_bf16_f32 v104, v116, v117
	v_cvt_pk_bf16_f32 v105, v118, v119
	v_cvt_pk_bf16_f32 v106, v108, v109
	v_cvt_pk_bf16_f32 v107, v110, v111
	global_store_dwordx4 v[112:113], v[104:107], off nt
	v_cvt_pk_bf16_f32 v96, v96, v97
	v_cvt_pk_bf16_f32 v97, v98, v99
	v_cvt_pk_bf16_f32 v98, v88, v89
	v_or_b32_e32 v88, 32, v148
	v_mad_i64_i32 v[88:89], s[18:19], v88, s11, v[138:139]
	v_cvt_pk_bf16_f32 v99, v90, v91
	global_store_dwordx4 v[112:113], v[96:99], off offset:256 nt
	s_nop 1
	v_lshl_add_u64 v[96:97], v[88:89], 0, v[140:141]
	v_cvt_pk_bf16_f32 v88, v100, v101
	v_cvt_pk_bf16_f32 v89, v102, v103
	v_cvt_pk_bf16_f32 v90, v92, v93
	v_cvt_pk_bf16_f32 v91, v94, v95
	global_store_dwordx4 v[96:97], v[88:91], off nt
	v_cvt_pk_bf16_f32 v80, v80, v81
	v_cvt_pk_bf16_f32 v81, v82, v83
	v_cvt_pk_bf16_f32 v82, v72, v73
	v_or_b32_e32 v72, 48, v148
	v_mad_i64_i32 v[72:73], s[18:19], v72, s11, v[138:139]
	v_cvt_pk_bf16_f32 v83, v74, v75
	global_store_dwordx4 v[96:97], v[80:83], off offset:256 nt
	s_nop 1
	v_lshl_add_u64 v[80:81], v[72:73], 0, v[140:141]
	v_cvt_pk_bf16_f32 v72, v84, v85
	v_cvt_pk_bf16_f32 v73, v86, v87
	v_cvt_pk_bf16_f32 v74, v76, v77
	v_cvt_pk_bf16_f32 v75, v78, v79
	global_store_dwordx4 v[80:81], v[72:75], off nt
	v_cvt_pk_bf16_f32 v68, v68, v69
	v_cvt_pk_bf16_f32 v69, v70, v71
	v_cvt_pk_bf16_f32 v70, v64, v65
	v_add_u32_e32 v64, 0x80, v148
	v_mad_i64_i32 v[64:65], s[18:19], v64, s11, v[138:139]
	v_lshl_add_u64 v[64:65], v[64:65], 0, v[140:141]
	v_cvt_pk_bf16_f32 v71, v66, v67
	global_store_dwordx4 v[80:81], v[68:71], off offset:256 nt
	v_cvt_pk_bf16_f32 v60, v60, v61
	v_cvt_pk_bf16_f32 v61, v62, v63
	v_cvt_pk_bf16_f32 v62, v56, v57
	v_cvt_pk_bf16_f32 v63, v58, v59
	global_store_dwordx4 v[64:65], v[60:63], off nt
	v_cvt_pk_bf16_f32 v48, v48, v49
	v_cvt_pk_bf16_f32 v49, v50, v51
	v_cvt_pk_bf16_f32 v50, v40, v41
	v_add_u32_e32 v40, 0x90, v148
	v_mad_i64_i32 v[40:41], s[18:19], v40, s11, v[138:139]
	v_cvt_pk_bf16_f32 v51, v42, v43
	global_store_dwordx4 v[64:65], v[48:51], off offset:256 nt
	s_nop 1
	v_lshl_add_u64 v[48:49], v[40:41], 0, v[140:141]
	v_cvt_pk_bf16_f32 v40, v52, v53
	v_cvt_pk_bf16_f32 v41, v54, v55
	v_cvt_pk_bf16_f32 v42, v44, v45
	v_cvt_pk_bf16_f32 v43, v46, v47
	global_store_dwordx4 v[48:49], v[40:43], off nt
	v_cvt_pk_bf16_f32 v32, v32, v33
	v_cvt_pk_bf16_f32 v33, v34, v35
	v_cvt_pk_bf16_f32 v34, v24, v25
	v_add_u32_e32 v24, 0xa0, v148
	v_mad_i64_i32 v[24:25], s[18:19], v24, s11, v[138:139]
	v_cvt_pk_bf16_f32 v35, v26, v27
	global_store_dwordx4 v[48:49], v[32:35], off offset:256 nt
	s_nop 1
	v_lshl_add_u64 v[32:33], v[24:25], 0, v[140:141]
	v_cvt_pk_bf16_f32 v24, v36, v37
	v_cvt_pk_bf16_f32 v25, v38, v39
	v_cvt_pk_bf16_f32 v26, v28, v29
	v_cvt_pk_bf16_f32 v27, v30, v31
	global_store_dwordx4 v[32:33], v[24:27], off nt
	v_cvt_pk_bf16_f32 v16, v16, v17
	v_cvt_pk_bf16_f32 v17, v18, v19
	v_cvt_pk_bf16_f32 v18, v8, v9
	v_add_u32_e32 v8, 0xb0, v148
	v_mad_i64_i32 v[8:9], s[18:19], v8, s11, v[138:139]
	v_cvt_pk_bf16_f32 v19, v10, v11
	global_store_dwordx4 v[32:33], v[16:19], off offset:256 nt
	s_nop 1
	v_lshl_add_u64 v[16:17], v[8:9], 0, v[140:141]
	v_cvt_pk_bf16_f32 v8, v20, v21
	v_cvt_pk_bf16_f32 v9, v22, v23
	v_cvt_pk_bf16_f32 v10, v12, v13
	v_cvt_pk_bf16_f32 v11, v14, v15
	global_store_dwordx4 v[16:17], v[8:11], off nt
	v_cvt_pk_bf16_f32 v4, v4, v5
	v_cvt_pk_bf16_f32 v5, v6, v7
	v_cvt_pk_bf16_f32 v6, v0, v1
	v_cvt_pk_bf16_f32 v7, v2, v3
	global_store_dwordx4 v[16:17], v[4:7], off offset:256 nt
	s_cbranch_vccnz .LBB0_234
	s_andn2_b64 vcc, exec, s[2:3]
	s_cbranch_vccnz .LBB0_233
	s_barrier
	s_branch .LBB0_233

; __device__ __forceinline__ unsigned cvt_pk_bf16(float lo, float hi) { unsigned r; asm volatile("v_cvt_pk_bf16_f32 %0, %1, %2" : "=v"(r) : "v"(lo), "v"(hi)); return r; }
;     DI void operator()(const pg8::f32x4 (&acc)[2][2][4][2], const pg8::Unit& u, int wr, int wc, int fr, int fq) const {
;         const int row0 = u.pm * 256 + wr * 64 + fr, col0 = u.pn * 128 + wc * 32 + 8 * fq;
; #pragma unroll
;         for (int ai = 0; ai < 2; ++ai)
; #pragma unroll
;             for (int m = 0; m < 4; ++m) { bf16* rowp = O + (size_t)(row0 + ai * 128 + m * 16) * FF + col0;
;                 float hv[8];
; #pragma unroll
;                 for (int n = 0; n < 2; ++n)
; #pragma unroll
;                     for (int j = 0; j < 4; ++j) { const float g = acc[ai][0][m][n][j], up = acc[ai][1][m][n][j]; hv[4 * n + j] = g * __builtin_amdgcn_rcpf(1.f + __expf(-g)) * up; }
;                 v4u w; w.x = pg8::cvt_pk_bf16(hv[0], hv[1]); w.y = pg8::cvt_pk_bf16(hv[2], hv[3]); w.z = pg8::cvt_pk_bf16(hv[4], hv[5]); w.w = pg8::cvt_pk_bf16(hv[6], hv[7]);
;                 *(v4u*)rowp = w; }
.LBB0_1179:
	v_mul_f32_e32 v145, 0xbfb8aa3b, v124
	v_exp_f32_e32 v145, v145
	v_lshl_or_b32 v146, s33, 7, v142
	v_lshl_add_u32 v144, s34, 8, v140
	v_ashrrev_i32_e32 v147, 31, v146
	v_add_f32_e32 v145, 1.0, v145
	v_rcp_f32_e32 v145, v145
	v_mov_b64_e32 v[138:139], s[2:3]
	s_movk_i32 s7, 0x1600
	v_mad_i64_i32 v[148:149], s[14:15], v144, s7, v[138:139]
	v_mul_f32_e32 v124, v124, v145
	v_mul_f32_e32 v120, v124, v120
	v_mul_f32_e32 v124, 0xbfb8aa3b, v125
	v_exp_f32_e32 v124, v124
	s_andn2_b64 vcc, exec, s[42:43]
	v_add_f32_e32 v124, 1.0, v124
	v_rcp_f32_e32 v124, v124
	s_nop 0
	v_mul_f32_e32 v124, v125, v124
	v_mul_f32_e32 v121, v124, v121
	v_mul_f32_e32 v124, 0xbfb8aa3b, v126
	v_exp_f32_e32 v124, v124
	s_nop 0
	v_add_f32_e32 v124, 1.0, v124
	v_rcp_f32_e32 v124, v124
	s_nop 0
	v_mul_f32_e32 v124, v126, v124
	v_mul_f32_e32 v122, v124, v122
	v_mul_f32_e32 v124, 0xbfb8aa3b, v127
	v_exp_f32_e32 v124, v124
	s_nop 0
	v_add_f32_e32 v124, 1.0, v124
	v_rcp_f32_e32 v124, v124
	s_nop 0
	v_mul_f32_e32 v124, v127, v124
	v_mul_f32_e32 v123, v124, v123
	v_mul_f32_e32 v124, 0xbfb8aa3b, v116
	v_exp_f32_e32 v124, v124
	s_nop 0
	v_add_f32_e32 v124, 1.0, v124
	v_rcp_f32_e32 v124, v124
	s_nop 0
	v_mul_f32_e32 v116, v116, v124
	v_mul_f32_e32 v116, v116, v112
	v_mul_f32_e32 v112, 0xbfb8aa3b, v117
	v_exp_f32_e32 v112, v112
	s_nop 0
	v_add_f32_e32 v112, 1.0, v112
	v_rcp_f32_e32 v112, v112
	s_nop 0
	v_mul_f32_e32 v112, v117, v112
	v_mul_f32_e32 v117, v112, v113
	v_mul_f32_e32 v112, 0xbfb8aa3b, v118
	v_exp_f32_e32 v112, v112
	s_nop 0
	v_add_f32_e32 v112, 1.0, v112
	v_rcp_f32_e32 v112, v112
	s_nop 0
	v_mul_f32_e32 v112, v118, v112
	v_mul_f32_e32 v124, v112, v114
	v_mul_f32_e32 v112, 0xbfb8aa3b, v119
	v_exp_f32_e32 v112, v112
	v_cvt_pk_bf16_f32 v114, v120, v121
	s_nop 0
	v_add_f32_e32 v112, 1.0, v112
	v_rcp_f32_e32 v112, v112
	s_nop 0
	v_mul_f32_e32 v112, v119, v112
	v_mul_f32_e32 v125, v112, v115
	v_lshlrev_b64 v[112:113], 1, v[146:147]
	v_lshl_add_u64 v[118:119], v[148:149], 0, v[112:113]
	v_cvt_pk_bf16_f32 v115, v122, v123
	v_cvt_pk_bf16_f32 v116, v116, v117
	v_cvt_pk_bf16_f32 v117, v124, v125
	global_store_dwordx4 v[118:119], v[114:117], off nt
	s_nop 1
	v_mul_f32_e32 v116, 0xbfb8aa3b, v108
	v_exp_f32_e32 v116, v116
	v_or_b32_e32 v114, 16, v144
	v_mad_i64_i32 v[114:115], s[14:15], v114, s7, v[138:139]
	v_add_f32_e32 v116, 1.0, v116
	v_rcp_f32_e32 v116, v116
	s_nop 0
	v_mul_f32_e32 v108, v108, v116
	v_mul_f32_e32 v104, v108, v104
	v_mul_f32_e32 v108, 0xbfb8aa3b, v109
	v_exp_f32_e32 v108, v108
	s_nop 0
	v_add_f32_e32 v108, 1.0, v108
	v_rcp_f32_e32 v108, v108
	s_nop 0
	v_mul_f32_e32 v108, v109, v108
	v_mul_f32_e32 v105, v108, v105
	v_mul_f32_e32 v108, 0xbfb8aa3b, v110
	v_exp_f32_e32 v108, v108
	s_nop 0
	v_add_f32_e32 v108, 1.0, v108
	v_rcp_f32_e32 v108, v108
	s_nop 0
	v_mul_f32_e32 v108, v110, v108
	v_mul_f32_e32 v106, v108, v106
	v_mul_f32_e32 v108, 0xbfb8aa3b, v111
	v_exp_f32_e32 v108, v108
	s_nop 0
	v_add_f32_e32 v108, 1.0, v108
	v_rcp_f32_e32 v108, v108
	s_nop 0
	v_mul_f32_e32 v108, v111, v108
	v_mul_f32_e32 v107, v108, v107
	v_mul_f32_e32 v108, 0xbfb8aa3b, v100
	v_exp_f32_e32 v108, v108
	s_nop 0
	v_add_f32_e32 v108, 1.0, v108
	v_rcp_f32_e32 v108, v108
	s_nop 0
	v_mul_f32_e32 v100, v100, v108
	v_mul_f32_e32 v108, v100, v96
	v_mul_f32_e32 v96, 0xbfb8aa3b, v101
	v_exp_f32_e32 v96, v96
	s_nop 0
	v_add_f32_e32 v96, 1.0, v96
	v_rcp_f32_e32 v96, v96
	s_nop 0
	v_mul_f32_e32 v96, v101, v96
	v_mul_f32_e32 v109, v96, v97
	v_mul_f32_e32 v96, 0xbfb8aa3b, v102
	v_exp_f32_e32 v96, v96
	v_lshl_add_u64 v[100:101], v[114:115], 0, v[112:113]
	v_add_f32_e32 v96, 1.0, v96
	v_rcp_f32_e32 v96, v96
	s_nop 0
	v_mul_f32_e32 v96, v102, v96
	v_mul_f32_e32 v102, v96, v98
	v_mul_f32_e32 v96, 0xbfb8aa3b, v103
	v_exp_f32_e32 v96, v96
	s_nop 0
	v_add_f32_e32 v96, 1.0, v96
	v_rcp_f32_e32 v96, v96
	s_nop 0
	v_mul_f32_e32 v96, v103, v96
	v_mul_f32_e32 v99, v96, v99
	v_cvt_pk_bf16_f32 v96, v104, v105
	v_cvt_pk_bf16_f32 v97, v106, v107
	v_cvt_pk_bf16_f32 v98, v108, v109
	v_cvt_pk_bf16_f32 v99, v102, v99
	global_store_dwordx4 v[100:101], v[96:99], off nt
	s_nop 1
	v_mul_f32_e32 v98, 0xbfb8aa3b, v92
	v_exp_f32_e32 v98, v98
	v_or_b32_e32 v96, 32, v144
	v_mad_i64_i32 v[96:97], s[14:15], v96, s7, v[138:139]
	v_add_f32_e32 v98, 1.0, v98
	v_rcp_f32_e32 v98, v98
	s_nop 0
	v_mul_f32_e32 v92, v92, v98
	v_mul_f32_e32 v88, v92, v88
	v_mul_f32_e32 v92, 0xbfb8aa3b, v93
	v_exp_f32_e32 v92, v92
	s_nop 0
	v_add_f32_e32 v92, 1.0, v92
	v_rcp_f32_e32 v92, v92
	s_nop 0
	v_mul_f32_e32 v92, v93, v92
	v_mul_f32_e32 v89, v92, v89
	v_mul_f32_e32 v92, 0xbfb8aa3b, v94
	v_exp_f32_e32 v92, v92
	s_nop 0
	v_add_f32_e32 v92, 1.0, v92
	v_rcp_f32_e32 v92, v92
	s_nop 0
	v_mul_f32_e32 v92, v94, v92
	v_mul_f32_e32 v90, v92, v90
	v_mul_f32_e32 v92, 0xbfb8aa3b, v95
	v_exp_f32_e32 v92, v92
	s_nop 0
	v_add_f32_e32 v92, 1.0, v92
	v_rcp_f32_e32 v92, v92
	s_nop 0
	v_mul_f32_e32 v92, v95, v92
	v_mul_f32_e32 v91, v92, v91
	v_mul_f32_e32 v92, 0xbfb8aa3b, v84
	v_exp_f32_e32 v92, v92
	s_nop 0
	v_add_f32_e32 v92, 1.0, v92
	v_rcp_f32_e32 v92, v92
	s_nop 0
	v_mul_f32_e32 v84, v84, v92
	v_mul_f32_e32 v92, v84, v80
	v_mul_f32_e32 v80, 0xbfb8aa3b, v85
	v_exp_f32_e32 v80, v80
	s_nop 0
	v_add_f32_e32 v80, 1.0, v80
	v_rcp_f32_e32 v80, v80
	s_nop 0
	v_mul_f32_e32 v80, v85, v80
	v_mul_f32_e32 v93, v80, v81
	v_mul_f32_e32 v80, 0xbfb8aa3b, v86
	v_exp_f32_e32 v80, v80
	v_lshl_add_u64 v[84:85], v[96:97], 0, v[112:113]
	v_add_f32_e32 v80, 1.0, v80
	v_rcp_f32_e32 v80, v80
	s_nop 0
	v_mul_f32_e32 v80, v86, v80
	v_mul_f32_e32 v86, v80, v82
	v_mul_f32_e32 v80, 0xbfb8aa3b, v87
	v_exp_f32_e32 v80, v80
	s_nop 0
	v_add_f32_e32 v80, 1.0, v80
	v_rcp_f32_e32 v80, v80
	s_nop 0
; __device__ __forceinline__ unsigned cvt_pk_bf16(float lo, float hi) { unsigned r; asm volatile("v_cvt_pk_bf16_f32 %0, %1, %2" : "=v"(r) : "v"(lo), "v"(hi)); return r; }
;     DI void operator()(const pg8::f32x4 (&acc)[2][2][4][2], const pg8::Unit& u, int wr, int wc, int fr, int fq) const {
;         const int row0 = u.pm * 256 + wr * 64 + fr, col0 = u.pn * 128 + wc * 32 + 8 * fq;
; #pragma unroll
;         for (int ai = 0; ai < 2; ++ai)
; #pragma unroll
;             for (int m = 0; m < 4; ++m) { bf16* rowp = O + (size_t)(row0 + ai * 128 + m * 16) * FF + col0;
;                 float hv[8];
; #pragma unroll
;                 for (int n = 0; n < 2; ++n)
; #pragma unroll
;                     for (int j = 0; j < 4; ++j) { const float g = acc[ai][0][m][n][j], up = acc[ai][1][m][n][j]; hv[4 * n + j] = g * __builtin_amdgcn_rcpf(1.f + __expf(-g)) * up; }
;                 v4u w; w.x = pg8::cvt_pk_bf16(hv[0], hv[1]); w.y = pg8::cvt_pk_bf16(hv[2], hv[3]); w.z = pg8::cvt_pk_bf16(hv[4], hv[5]); w.w = pg8::cvt_pk_bf16(hv[6], hv[7]);
;                 *(v4u*)rowp = w; }
	v_mul_f32_e32 v80, v87, v80
	v_mul_f32_e32 v83, v80, v83
	v_cvt_pk_bf16_f32 v80, v88, v89
	v_cvt_pk_bf16_f32 v81, v90, v91
	v_cvt_pk_bf16_f32 v82, v92, v93
	v_cvt_pk_bf16_f32 v83, v86, v83
	global_store_dwordx4 v[84:85], v[80:83], off nt
	s_nop 1
	v_mul_f32_e32 v82, 0xbfb8aa3b, v76
	v_exp_f32_e32 v82, v82
	v_or_b32_e32 v80, 48, v144
	v_mad_i64_i32 v[80:81], s[14:15], v80, s7, v[138:139]
	v_add_f32_e32 v82, 1.0, v82
	v_rcp_f32_e32 v82, v82
	s_nop 0
	v_mul_f32_e32 v76, v76, v82
	v_mul_f32_e32 v72, v76, v72
	v_mul_f32_e32 v76, 0xbfb8aa3b, v77
	v_exp_f32_e32 v76, v76
	s_nop 0
	v_add_f32_e32 v76, 1.0, v76
	v_rcp_f32_e32 v76, v76
	s_nop 0
	v_mul_f32_e32 v76, v77, v76
	v_mul_f32_e32 v73, v76, v73
	v_mul_f32_e32 v76, 0xbfb8aa3b, v78
	v_exp_f32_e32 v76, v76
	s_nop 0
	v_add_f32_e32 v76, 1.0, v76
	v_rcp_f32_e32 v76, v76
	s_nop 0
	v_mul_f32_e32 v76, v78, v76
	v_mul_f32_e32 v74, v76, v74
	v_mul_f32_e32 v76, 0xbfb8aa3b, v79
	v_exp_f32_e32 v76, v76
	s_nop 0
	v_add_f32_e32 v76, 1.0, v76
	v_rcp_f32_e32 v76, v76
	s_nop 0
	v_mul_f32_e32 v76, v79, v76
	v_mul_f32_e32 v75, v76, v75
	v_mul_f32_e32 v76, 0xbfb8aa3b, v68
	v_exp_f32_e32 v76, v76
	s_nop 0
	v_add_f32_e32 v76, 1.0, v76
	v_rcp_f32_e32 v76, v76
	s_nop 0
	v_mul_f32_e32 v68, v68, v76
	v_mul_f32_e32 v76, v68, v64
	v_mul_f32_e32 v64, 0xbfb8aa3b, v69
	v_exp_f32_e32 v64, v64
	s_nop 0
	v_add_f32_e32 v64, 1.0, v64
	v_rcp_f32_e32 v64, v64
	s_nop 0
	v_mul_f32_e32 v64, v69, v64
	v_mul_f32_e32 v77, v64, v65
	v_mul_f32_e32 v64, 0xbfb8aa3b, v70
	v_exp_f32_e32 v64, v64
	v_lshl_add_u64 v[68:69], v[80:81], 0, v[112:113]
	v_add_f32_e32 v64, 1.0, v64
	v_rcp_f32_e32 v64, v64
	s_nop 0
	v_mul_f32_e32 v64, v70, v64
	v_mul_f32_e32 v70, v64, v66
	v_mul_f32_e32 v64, 0xbfb8aa3b, v71
	v_exp_f32_e32 v64, v64
	s_nop 0
	v_add_f32_e32 v64, 1.0, v64
	v_rcp_f32_e32 v64, v64
	s_nop 0
	v_mul_f32_e32 v64, v71, v64
	v_mul_f32_e32 v67, v64, v67
	v_cvt_pk_bf16_f32 v64, v72, v73
	v_cvt_pk_bf16_f32 v65, v74, v75
	v_cvt_pk_bf16_f32 v66, v76, v77
	v_cvt_pk_bf16_f32 v67, v70, v67
	global_store_dwordx4 v[68:69], v[64:67], off nt
	s_nop 1
	v_mul_f32_e32 v66, 0xbfb8aa3b, v60
	v_exp_f32_e32 v66, v66
	v_add_u32_e32 v64, 0x80, v144
	v_mad_i64_i32 v[64:65], s[14:15], v64, s7, v[138:139]
	v_add_f32_e32 v66, 1.0, v66
	v_rcp_f32_e32 v66, v66
	s_nop 0
	v_mul_f32_e32 v60, v60, v66
	v_mul_f32_e32 v56, v60, v56
	v_mul_f32_e32 v60, 0xbfb8aa3b, v61
	v_exp_f32_e32 v60, v60
	s_nop 0
	v_add_f32_e32 v60, 1.0, v60
	v_rcp_f32_e32 v60, v60
	s_nop 0
	v_mul_f32_e32 v60, v61, v60
	v_mul_f32_e32 v57, v60, v57
	v_mul_f32_e32 v60, 0xbfb8aa3b, v62
	v_exp_f32_e32 v60, v60
	s_nop 0
	v_add_f32_e32 v60, 1.0, v60
	v_rcp_f32_e32 v60, v60
	s_nop 0
	v_mul_f32_e32 v60, v62, v60
	v_mul_f32_e32 v58, v60, v58
	v_mul_f32_e32 v60, 0xbfb8aa3b, v63
	v_exp_f32_e32 v60, v60
	s_nop 0
	v_add_f32_e32 v60, 1.0, v60
	v_rcp_f32_e32 v60, v60
	s_nop 0
	v_mul_f32_e32 v60, v63, v60
	v_mul_f32_e32 v59, v60, v59
	v_mul_f32_e32 v60, 0xbfb8aa3b, v52
	v_exp_f32_e32 v60, v60
	s_nop 0
	v_add_f32_e32 v60, 1.0, v60
	v_rcp_f32_e32 v60, v60
	s_nop 0
	v_mul_f32_e32 v52, v52, v60
	v_mul_f32_e32 v60, v52, v48
	v_mul_f32_e32 v48, 0xbfb8aa3b, v53
	v_exp_f32_e32 v48, v48
	s_nop 0
	v_add_f32_e32 v48, 1.0, v48
	v_rcp_f32_e32 v48, v48
	s_nop 0
	v_mul_f32_e32 v48, v53, v48
	v_mul_f32_e32 v61, v48, v49
	v_mul_f32_e32 v48, 0xbfb8aa3b, v54
	v_exp_f32_e32 v48, v48
	v_lshl_add_u64 v[52:53], v[64:65], 0, v[112:113]
	v_add_f32_e32 v48, 1.0, v48
	v_rcp_f32_e32 v48, v48
	s_nop 0
	v_mul_f32_e32 v48, v54, v48
	v_mul_f32_e32 v54, v48, v50
	v_mul_f32_e32 v48, 0xbfb8aa3b, v55
	v_exp_f32_e32 v48, v48
	s_nop 0
	v_add_f32_e32 v48, 1.0, v48
	v_rcp_f32_e32 v48, v48
	s_nop 0
	v_mul_f32_e32 v48, v55, v48
	v_mul_f32_e32 v51, v48, v51
	v_cvt_pk_bf16_f32 v48, v56, v57
	v_cvt_pk_bf16_f32 v49, v58, v59
	v_cvt_pk_bf16_f32 v50, v60, v61
	v_cvt_pk_bf16_f32 v51, v54, v51
	global_store_dwordx4 v[52:53], v[48:51], off nt
	s_nop 1
	v_mul_f32_e32 v50, 0xbfb8aa3b, v44
	v_exp_f32_e32 v50, v50
	v_add_u32_e32 v48, 0x90, v144
	v_mad_i64_i32 v[48:49], s[14:15], v48, s7, v[138:139]
	v_add_f32_e32 v50, 1.0, v50
	v_rcp_f32_e32 v50, v50
	s_nop 0
	v_mul_f32_e32 v44, v44, v50
	v_mul_f32_e32 v40, v44, v40
	v_mul_f32_e32 v44, 0xbfb8aa3b, v45
	v_exp_f32_e32 v44, v44
	s_nop 0
	v_add_f32_e32 v44, 1.0, v44
	v_rcp_f32_e32 v44, v44
	s_nop 0
	v_mul_f32_e32 v44, v45, v44
	v_mul_f32_e32 v41, v44, v41
	v_mul_f32_e32 v44, 0xbfb8aa3b, v46
	v_exp_f32_e32 v44, v44
	s_nop 0
	v_add_f32_e32 v44, 1.0, v44
	v_rcp_f32_e32 v44, v44
	s_nop 0
	v_mul_f32_e32 v44, v46, v44
	v_mul_f32_e32 v42, v44, v42
	v_mul_f32_e32 v44, 0xbfb8aa3b, v47
	v_exp_f32_e32 v44, v44
	s_nop 0
	v_add_f32_e32 v44, 1.0, v44
	v_rcp_f32_e32 v44, v44
	s_nop 0
	v_mul_f32_e32 v44, v47, v44
; __device__ __forceinline__ unsigned cvt_pk_bf16(float lo, float hi) { unsigned r; asm volatile("v_cvt_pk_bf16_f32 %0, %1, %2" : "=v"(r) : "v"(lo), "v"(hi)); return r; }
;     DI void operator()(const pg8::f32x4 (&acc)[2][2][4][2], const pg8::Unit& u, int wr, int wc, int fr, int fq) const {
;         const int row0 = u.pm * 256 + wr * 64 + fr, col0 = u.pn * 128 + wc * 32 + 8 * fq;
; #pragma unroll
;         for (int ai = 0; ai < 2; ++ai)
; #pragma unroll
;             for (int m = 0; m < 4; ++m) { bf16* rowp = O + (size_t)(row0 + ai * 128 + m * 16) * FF + col0;
;                 float hv[8];
; #pragma unroll
;                 for (int n = 0; n < 2; ++n)
; #pragma unroll
;                     for (int j = 0; j < 4; ++j) { const float g = acc[ai][0][m][n][j], up = acc[ai][1][m][n][j]; hv[4 * n + j] = g * __builtin_amdgcn_rcpf(1.f + __expf(-g)) * up; }
;                 v4u w; w.x = pg8::cvt_pk_bf16(hv[0], hv[1]); w.y = pg8::cvt_pk_bf16(hv[2], hv[3]); w.z = pg8::cvt_pk_bf16(hv[4], hv[5]); w.w = pg8::cvt_pk_bf16(hv[6], hv[7]);
;                 *(v4u*)rowp = w; }
	v_mul_f32_e32 v43, v44, v43
	v_mul_f32_e32 v44, 0xbfb8aa3b, v36
	v_exp_f32_e32 v44, v44
	s_nop 0
	v_add_f32_e32 v44, 1.0, v44
	v_rcp_f32_e32 v44, v44
	s_nop 0
	v_mul_f32_e32 v36, v36, v44
	v_mul_f32_e32 v44, v36, v32
	v_mul_f32_e32 v32, 0xbfb8aa3b, v37
	v_exp_f32_e32 v32, v32
	s_nop 0
	v_add_f32_e32 v32, 1.0, v32
	v_rcp_f32_e32 v32, v32
	s_nop 0
	v_mul_f32_e32 v32, v37, v32
	v_mul_f32_e32 v45, v32, v33
	v_mul_f32_e32 v32, 0xbfb8aa3b, v38
	v_exp_f32_e32 v32, v32
	v_lshl_add_u64 v[36:37], v[48:49], 0, v[112:113]
	v_add_f32_e32 v32, 1.0, v32
	v_rcp_f32_e32 v32, v32
	s_nop 0
	v_mul_f32_e32 v32, v38, v32
	v_mul_f32_e32 v38, v32, v34
	v_mul_f32_e32 v32, 0xbfb8aa3b, v39
	v_exp_f32_e32 v32, v32
	s_nop 0
	v_add_f32_e32 v32, 1.0, v32
	v_rcp_f32_e32 v32, v32
	s_nop 0
	v_mul_f32_e32 v32, v39, v32
	v_mul_f32_e32 v35, v32, v35
	v_cvt_pk_bf16_f32 v32, v40, v41
	v_cvt_pk_bf16_f32 v33, v42, v43
	v_cvt_pk_bf16_f32 v34, v44, v45
	v_cvt_pk_bf16_f32 v35, v38, v35
	global_store_dwordx4 v[36:37], v[32:35], off nt
	s_nop 1
	v_mul_f32_e32 v34, 0xbfb8aa3b, v28
	v_exp_f32_e32 v34, v34
	v_add_u32_e32 v32, 0xa0, v144
	v_mad_i64_i32 v[32:33], s[14:15], v32, s7, v[138:139]
	v_add_f32_e32 v34, 1.0, v34
	v_rcp_f32_e32 v34, v34
	s_nop 0
	v_mul_f32_e32 v28, v28, v34
	v_mul_f32_e32 v24, v28, v24
	v_mul_f32_e32 v28, 0xbfb8aa3b, v29
	v_exp_f32_e32 v28, v28
	s_nop 0
	v_add_f32_e32 v28, 1.0, v28
	v_rcp_f32_e32 v28, v28
	s_nop 0
	v_mul_f32_e32 v28, v29, v28
	v_mul_f32_e32 v25, v28, v25
	v_mul_f32_e32 v28, 0xbfb8aa3b, v30
	v_exp_f32_e32 v28, v28
	s_nop 0
	v_add_f32_e32 v28, 1.0, v28
	v_rcp_f32_e32 v28, v28
	s_nop 0
	v_mul_f32_e32 v28, v30, v28
	v_mul_f32_e32 v26, v28, v26
	v_mul_f32_e32 v28, 0xbfb8aa3b, v31
	v_exp_f32_e32 v28, v28
	s_nop 0
	v_add_f32_e32 v28, 1.0, v28
	v_rcp_f32_e32 v28, v28
	s_nop 0
	v_mul_f32_e32 v28, v31, v28
	v_mul_f32_e32 v27, v28, v27
	v_mul_f32_e32 v28, 0xbfb8aa3b, v20
	v_exp_f32_e32 v28, v28
	s_nop 0
	v_add_f32_e32 v28, 1.0, v28
	v_rcp_f32_e32 v28, v28
	s_nop 0
	v_mul_f32_e32 v20, v20, v28
	v_mul_f32_e32 v28, v20, v16
	v_mul_f32_e32 v16, 0xbfb8aa3b, v21
	v_exp_f32_e32 v16, v16
	s_nop 0
	v_add_f32_e32 v16, 1.0, v16
	v_rcp_f32_e32 v16, v16
	s_nop 0
	v_mul_f32_e32 v16, v21, v16
	v_mul_f32_e32 v29, v16, v17
	v_mul_f32_e32 v16, 0xbfb8aa3b, v22
	v_exp_f32_e32 v16, v16
	v_lshl_add_u64 v[20:21], v[32:33], 0, v[112:113]
	v_add_f32_e32 v16, 1.0, v16
	v_rcp_f32_e32 v16, v16
	s_nop 0
	v_mul_f32_e32 v16, v22, v16
	v_mul_f32_e32 v22, v16, v18
	v_mul_f32_e32 v16, 0xbfb8aa3b, v23
	v_exp_f32_e32 v16, v16
	s_nop 0
	v_add_f32_e32 v16, 1.0, v16
	v_rcp_f32_e32 v16, v16
	s_nop 0
	v_mul_f32_e32 v16, v23, v16
	v_mul_f32_e32 v19, v16, v19
	v_cvt_pk_bf16_f32 v16, v24, v25
	v_cvt_pk_bf16_f32 v17, v26, v27
	v_cvt_pk_bf16_f32 v18, v28, v29
	v_cvt_pk_bf16_f32 v19, v22, v19
	global_store_dwordx4 v[20:21], v[16:19], off nt
	s_nop 1
	v_mul_f32_e32 v18, 0xbfb8aa3b, v12
	v_exp_f32_e32 v18, v18
	v_add_u32_e32 v16, 0xb0, v144
	v_mad_i64_i32 v[16:17], s[14:15], v16, s7, v[138:139]
	v_add_f32_e32 v18, 1.0, v18
	v_rcp_f32_e32 v18, v18
	s_mov_b64 s[14:15], -1
	v_mul_f32_e32 v12, v12, v18
	v_mul_f32_e32 v8, v12, v8
	v_mul_f32_e32 v12, 0xbfb8aa3b, v13
	v_exp_f32_e32 v12, v12
	s_nop 0
	v_add_f32_e32 v12, 1.0, v12
	v_rcp_f32_e32 v12, v12
	s_nop 0
	v_mul_f32_e32 v12, v13, v12
	v_mul_f32_e32 v9, v12, v9
	v_mul_f32_e32 v12, 0xbfb8aa3b, v14
	v_exp_f32_e32 v12, v12
	s_nop 0
	v_add_f32_e32 v12, 1.0, v12
	v_rcp_f32_e32 v12, v12
	s_nop 0
	v_mul_f32_e32 v12, v14, v12
	v_mul_f32_e32 v10, v12, v10
	v_mul_f32_e32 v12, 0xbfb8aa3b, v15
	v_exp_f32_e32 v12, v12
	s_nop 0
	v_add_f32_e32 v12, 1.0, v12
	v_rcp_f32_e32 v12, v12
	s_nop 0
	v_mul_f32_e32 v12, v15, v12
	v_mul_f32_e32 v11, v12, v11
	v_mul_f32_e32 v12, 0xbfb8aa3b, v4
	v_exp_f32_e32 v12, v12
	s_nop 0
	v_add_f32_e32 v12, 1.0, v12
	v_rcp_f32_e32 v12, v12
	s_nop 0
	v_mul_f32_e32 v4, v4, v12
	v_mul_f32_e32 v12, v4, v0
	v_mul_f32_e32 v0, 0xbfb8aa3b, v5
	v_exp_f32_e32 v0, v0
	s_nop 0
	v_add_f32_e32 v0, 1.0, v0
	v_rcp_f32_e32 v0, v0
	s_nop 0
	v_mul_f32_e32 v0, v5, v0
	v_mul_f32_e32 v13, v0, v1
	v_mul_f32_e32 v0, 0xbfb8aa3b, v6
	v_exp_f32_e32 v0, v0
	v_lshl_add_u64 v[4:5], v[16:17], 0, v[112:113]
	v_add_f32_e32 v0, 1.0, v0
	v_rcp_f32_e32 v0, v0
	s_nop 0
	v_mul_f32_e32 v0, v6, v0
	v_mul_f32_e32 v6, v0, v2
	v_mul_f32_e32 v0, 0xbfb8aa3b, v7
	v_exp_f32_e32 v0, v0
	s_nop 0
	v_add_f32_e32 v0, 1.0, v0
	v_rcp_f32_e32 v0, v0
	s_nop 0
	v_mul_f32_e32 v0, v7, v0
	v_mul_f32_e32 v3, v0, v3
	v_cvt_pk_bf16_f32 v0, v8, v9
	v_cvt_pk_bf16_f32 v1, v10, v11
	v_cvt_pk_bf16_f32 v2, v12, v13
	v_cvt_pk_bf16_f32 v3, v6, v3
	global_store_dwordx4 v[4:5], v[0:3], off nt
	s_cbranch_vccnz .LBB0_1172
	s_andn2_b64 vcc, exec, s[0:1]
	s_cbranch_vccnz .LBB0_1171
	s_barrier
	s_branch .LBB0_1171
